# P3 prompt-tile-first on workgroups 0-31, early decode units disabled (threshold 256)
# baseline (speedup 1.0000x reference)
; __device__ __forceinline__ int fresh_lane() { int l; asm volatile("v_mbcnt_lo_u32_b32 %0, -1, 0\n\tv_mbcnt_hi_u32_b32 %0, -1, %0" : "=v"(l)); return l; }
; #define SEAM(k) do { if (IN(k) && IN((k) + 1)) xcd_barrier(bar, C.wave); } while (0)
; #define PH5 { phase_attention(P, C, (P.pad >> 8) & 3, P.li); }
; #define RUN(k, BODY) do { if (IN(k)) { unsigned char* ws = P.ws; LAUNDER_GPTR(ws); BODY } } while (0)
; __device__ __forceinline__ void phase_attention(const Params& P, const Ctx& C, int parts, int qset) {
;     ...
;     for (int i = 0; i < 8; ++i) { const int x = (x0 + i) & 7;
;         for (;;) {
;             __syncthreads();
;             if (C.wave == 0 && fresh_lane() == 0) *slot = __hip_atomic_fetch_add(qc + 64 * x, 1u, __ATOMIC_RELAXED, __HIP_MEMORY_SCOPE_AGENT);
;             __syncthreads();
;             const unsigned u = *slot;
;             if (u >= 128u) break;
;             const int us = __builtin_amdgcn_readfirstlane((int)u);
; __global__ void __launch_bounds__(NWAVES * 64, 2) fwd_kernel(Params P) {
;     ...
;     RUN(3, PH3); SEAM(3);
;     RUN(4, PH4);
;     RUN(5, PH5); SEAM(5);
.LBB0_1136:
	s_bitcmp1_b32 s101, 1
	s_cbranch_scc1 .Lmy_e7
	s_bitset1_b32 s101, 1
	s_cmpk_lg_i32 s68, 0x100
	s_cbranch_scc1 .Lmy_e7
	s_bitset1_b32 s101, 3
	v_readlane_b32 s99, v254, 10
	s_cmpk_lt_u32 s99, 256
	s_cbranch_scc1 .Lmy_e7
	s_and_b32 s100, s99, 31
	s_mul_i32 s100, s100, 4
	s_add_i32 s100, s100, 1
	s_bitset1_b32 s101, 0
	s_waitcnt vmcnt(0)
	s_barrier
	s_mov_b64 s[2:3], -1
	s_branch .LBB0_1192

; __device__ __forceinline__ void phase_attention(const Params& P, const Ctx& C, int parts, int qset) {
;     ...
;             if (pq >= 0) { if (parts & 1) { if (fixed_ok) attn_prompt_unit<true>(P, C, x, pq); else attn_prompt_unit<false>(P, C, x, pq); } }
;             else { if (parts & 2) attn_decode_unit(P, C, x * 64 + dq); }
.LBB0_1215:
	s_bitcmp1_b32 s101, 0
	s_cbranch_scc1 .Lmy_e8
	s_bitcmp1_b32 s101, 3
	s_cbranch_scc0 .Lmy_e8
	v_readlane_b32 s99, v254, 13
	s_add_i32 s99, s99, s4
	s_cmpk_lt_u32 s99, 512
	s_cbranch_scc1 .Lmy_e8
	s_bitcmp0_b32 s4, 0
	s_cbranch_scc1 .LBB0_1200
